# XCD-local barriers (run-time checked placement) at the norm/SwiGLU/down seams, on top of chained MFMA order
# speedup vs baseline: 1.0251x; 1.0001x over previous
; #define LAS __attribute__((address_space(3)))
; __device__ __forceinline__ unsigned xb_add(unsigned* p, unsigned v) { return __hip_atomic_fetch_add(p, v, __ATOMIC_RELAXED, __HIP_MEMORY_SCOPE_AGENT); }
; __device__ __forceinline__ unsigned xb_xcc_id() { return (unsigned)__builtin_amdgcn_s_getreg((3 << 11) | 20) & 0xFu; }
; __device__ __forceinline__ XcdBarrier xcd_barrier_post(unsigned* bar, volatile LAS unsigned* st) {
;     XcdBarrier b; b.bar = bar; b.x = xb_xcc_id(); b.st = st; b.wv = 0;
;     if (threadIdx.x == 0) (void)xb_add(&bar[XB_XCNT(b.x)], 1u);
;     return b;
; __global__ void __launch_bounds__(NWAVES * 64, 2) hybrid_fwd(Args args) {
;     ...
;     const int tid = threadIdx.x, lane = tid & 63, wave = __builtin_amdgcn_readfirstlane(tid >> 6);
;     const int G = gridDim.x; const int bx = blockIdx.x; const int vcu = (G % 8 == 0) ? (bx % 8) * (G / 8) + bx / 8 : bx;
;     const int gw = vcu * NWAVES + wave, NGW = G * NWAVES;
;     unsigned char* ws = args.ws;
;     gu32* ctl = (gu32*)(ws + WS_CTL);
;     for (int u = tid; u < (LDS_BYTES - LDSCTL_OFF) / 4; u += NWAVES * 64) ((LAS unsigned*)(lds + LDSCTL_OFF))[u] = 0u;
;     __syncthreads();
;     XcdBarrier bar = xcd_barrier_post((unsigned*)(ctl + CW_BAR), MISC + 8); bar.wv = wave;
_Z10hybrid_fwd4Args:
	s_mov_b32 s100, 0
	v_writelane_b32 v255, s100, 60
	s_load_dword s72, s[0:1], 0x80
	s_add_u32 s4, s0, 0x80
	s_addc_u32 s5, s1, 0
	s_mov_b32 s9, s2
	v_writelane_b32 v255, s4, 0
	s_waitcnt lgkmcnt(0)
	s_and_b32 s3, s72, 7
	v_readfirstlane_b32 s2, v0
	v_writelane_b32 v255, s5, 1
	s_cmp_lg_u32 s3, 0
	v_writelane_b32 v255, s9, 2
	s_cbranch_scc1 .LBB0_2
	v_readlane_b32 s6, v255, 2
	s_ashr_i32 s4, s6, 31
	s_lshr_b32 s4, s4, 29
	s_add_i32 s4, s6, s4
	s_ashr_i32 s5, s4, 3
	s_and_b32 s4, s4, -8
	s_ashr_i32 s3, s72, 3
	s_sub_i32 s4, s6, s4
	s_mul_i32 s3, s3, s4
	s_add_i32 s9, s3, s5
.LBB0_2:
	v_lshl_add_u32 v63, v0, 2, 0
	v_mov_b32_e32 v2, 0
	v_add_u32_e32 v1, 0x20000, v63
	ds_write2st64_b32 v1, v2, v2 offset1:8
	ds_write2st64_b32 v1, v2, v2 offset0:16 offset1:24
	v_or_b32_e32 v1, 0x800, v0
	s_mov_b64 s[4:5], -1
	s_and_saveexec_b64 s[6:7], s[4:5]
	v_lshl_add_u32 v3, v1, 2, 0
	v_add_u32_e32 v3, 0x20000, v3
	ds_write_b32 v3, v2
	s_or_b64 exec, exec, s[6:7]
	s_and_saveexec_b64 s[6:7], s[4:5]
	s_add_i32 s3, 0, 0x20000
	v_lshl_add_u32 v1, v1, 2, s3
	v_mov_b32_e32 v2, 0
	ds_write_b32 v1, v2 offset:2048
	s_or_b64 exec, exec, s[6:7]
	v_or_b32_e32 v1, 0xc00, v0
	v_cmp_gt_u32_e64 s[28:29], 7, 6
	v_cmp_gt_u32_e64 s[30:31], 7, 5
	s_and_saveexec_b64 s[4:5], s[30:31]
	v_lshl_add_u32 v2, v1, 2, 0
	v_add_u32_e32 v2, 0x20000, v2
	v_mov_b32_e32 v3, 0
	ds_write_b32 v2, v3
	s_or_b64 exec, exec, s[4:5]
	s_load_dwordx16 s[12:27], s[0:1], 0x40
	s_waitcnt lgkmcnt(0)
	v_writelane_b32 v255, s12, 3
	s_nop 1
	v_writelane_b32 v255, s13, 4
	v_writelane_b32 v255, s14, 5
	v_writelane_b32 v255, s15, 6
	v_writelane_b32 v255, s16, 7
	v_writelane_b32 v255, s17, 8
	v_writelane_b32 v255, s18, 9
	v_writelane_b32 v255, s19, 10
	v_writelane_b32 v255, s20, 11
	v_writelane_b32 v255, s21, 12
	v_writelane_b32 v255, s22, 13
	v_writelane_b32 v255, s23, 14
	v_writelane_b32 v255, s24, 15
	v_writelane_b32 v255, s25, 16
	v_writelane_b32 v255, s26, 17
	v_writelane_b32 v255, s27, 18
	s_and_saveexec_b64 s[4:5], s[28:29]
	s_add_i32 s3, 0, 0x20000
	v_lshl_add_u32 v1, v1, 2, s3
	v_mov_b32_e32 v2, 0
	ds_write_b32 v1, v2 offset:2048
	s_or_b64 exec, exec, s[4:5]
	v_readlane_b32 s12, v255, 3
	s_load_dwordx16 s[36:51], s[0:1], 0x0
	v_readlane_b32 s26, v255, 17
	v_readlane_b32 s27, v255, 18
	s_add_u32 s0, s26, 0x4000
	s_addc_u32 s1, s27, 0
	v_readlane_b32 s13, v255, 4
	v_readlane_b32 s14, v255, 5
	v_readlane_b32 s15, v255, 6
	v_readlane_b32 s16, v255, 7
	v_readlane_b32 s17, v255, 8
	v_readlane_b32 s18, v255, 9
	v_readlane_b32 s19, v255, 10
	v_readlane_b32 s20, v255, 11
	v_readlane_b32 s21, v255, 12
	v_readlane_b32 s22, v255, 13
	v_readlane_b32 s23, v255, 14
	v_readlane_b32 s24, v255, 15
	v_readlane_b32 s25, v255, 16
	v_writelane_b32 v255, s0, 19
	s_waitcnt lgkmcnt(0)
	s_barrier
	v_writelane_b32 v255, s1, 20
	s_getreg_b32 s6, hwreg(HW_REG_XCC_ID, 0, 4)
	s_mov_b32 s3, 0
	v_cmp_eq_u32_e32 vcc, 0, v0
	s_and_saveexec_b64 s[0:1], vcc
	s_cbranch_execz .LBB0_13
	s_mov_b64 s[4:5], exec
	v_mbcnt_lo_u32_b32 v1, s4, 0
	v_mbcnt_hi_u32_b32 v1, s5, v1
	v_cmp_eq_u32_e32 vcc, 0, v1
	s_and_b64 s[10:11], exec, vcc
	s_mov_b64 exec, s[10:11]
	s_cbranch_execz .LBB0_13
	s_lshl_b32 s6, s6, 8
	s_bcnt1_i32_b64 s4, s[4:5]
	s_and_b32 s6, s6, 0xf00
	v_mov_b32_e32 v2, s4
	v_readlane_b32 s4, v255, 19
	v_mov_b32_e32 v1, s6
	v_readlane_b32 s5, v255, 20
	s_nop 4
	global_atomic_add v1, v2, s[4:5] offset:1024
	v_readlane_b32 s10, v255, 2
	s_nop 1
	s_and_b32 s10, s10, 7
	s_add_u32 s11, s10, 1
	s_sub_u32 s10, 8, s10
	v_add_u32_e32 v3, 0x4000, v1
	v_mov_b32_e32 v4, s11
	global_atomic_umax v3, v4, s[4:5]
	v_add_u32_e32 v3, 0x5000, v1
	v_mov_b32_e32 v4, s10
	s_nop 0
	global_atomic_umax v3, v4, s[4:5]

; __device__ __forceinline__ unsigned xb_ld(unsigned* p)              { return __hip_atomic_load(p, __ATOMIC_RELAXED, __HIP_MEMORY_SCOPE_AGENT); }
; __device__ __forceinline__ unsigned xb_add(unsigned* p, unsigned v) { return __hip_atomic_fetch_add(p, v, __ATOMIC_RELAXED, __HIP_MEMORY_SCOPE_AGENT); }
; #define XB_SPIN(cond, bar) do { unsigned _sp = 0; while (cond) { __builtin_amdgcn_s_sleep(1); \
;     if ((++_sp & 255u) == 0u) { if (xb_ld(&(bar)[XB_TMO])) break; if (_sp > XB_SPIN_CAP) { atomicAdd(&(bar)[XB_TMO], 1u); break; } } } } while (0)
; __device__ __forceinline__ int xb_lane() { int l; asm volatile("v_mbcnt_lo_u32_b32 %0, -1, 0\n\tv_mbcnt_hi_u32_b32 %0, -1, %0" : "=v"(l)); return l; }
; __device__ __forceinline__ void xcd_barrier(const XcdBarrier& b) {
;     asm volatile("s_waitcnt vmcnt(0)" ::: "memory");
;     __syncthreads();
;     if (b.wv == 0 && xb_lane() == 0) {
;         unsigned* bar = b.bar;
;         __builtin_amdgcn_s_waitcnt(0);
;         unsigned nloc = b.st[0], nx = b.st[1];
;         if (nloc == 0u) { xcd_barrier_complete(bar, b.x, nloc, nx); b.st[0] = nloc; b.st[1] = nx; }
;         const unsigned old = xb_add(&bar[XB_XSUB(b.x)], 1u);
;         const unsigned gen = old / nloc;
;         if (old + 1u == (gen + 1u) * nloc) {
;             __builtin_amdgcn_fence(__ATOMIC_RELEASE, "agent");
;             asm volatile("s_waitcnt vmcnt(0)" ::: "memory");
;             const unsigned og = xb_add(&bar[XB_TOP], 1u);
;             const unsigned tg = og / nx;
;             if (og + 1u == (tg + 1u) * nx) xb_add(&bar[XB_TOPGEN], 1u);
;             else XB_SPIN(xb_ld(&bar[XB_TOPGEN]) == tg, bar);
;             __builtin_amdgcn_fence(__ATOMIC_ACQUIRE, "agent");
;             xb_add(&bar[XB_XGEN(b.x)], 1u);
;             asm volatile("s_waitcnt vmcnt(0)" ::: "memory");
;         } else {
;             XB_SPIN(xb_ld(&bar[XB_XGEN(b.x)]) == gen, bar);
;             __builtin_amdgcn_fence(__ATOMIC_ACQUIRE, "agent");
;             asm volatile("s_waitcnt vmcnt(0)" ::: "memory");
;         }
;     }
;     __syncthreads();
; }
.LBB0_167:
	v_writelane_b32 v255, s7, 45
	s_mov_b32 s10, s11
	v_readlane_b32 s2, v255, 26
	v_readlane_b32 s3, v255, 27
	s_getreg_b32 s0, hwreg(HW_REG_XCC_ID, 0, 4)
	s_waitcnt vmcnt(0)
	s_andn2_b64 vcc, exec, s[2:3]
	v_cndmask_b32_e64 v0, 0, 1, s[2:3]
	v_cmp_ne_u32_e64 s[4:5], 1, v0
	s_barrier
	s_nop 0
	v_writelane_b32 v255, s4, 46
	s_nop 1
	v_writelane_b32 v255, s5, 47
	s_cbranch_vccnz .LBB0_221
	v_readlane_b32 s100, v255, 60
	s_nop 1
	s_cmp_lg_u32 s100, 0
	s_cbranch_scc1 .Lxb_nochk0
	s_mov_b64 s[100:101], exec
	s_mov_b64 exec, 1
	s_lshl_b32 s68, s0, 8
	v_readlane_b32 s8, v255, 19
	v_readlane_b32 s9, v255, 20
	s_add_u32 s69, s68, 0x4000
	s_add_u32 s70, s68, 0x5000
	s_add_u32 s71, s68, 0x400
	v_mov_b32_e32 v1, s69
	v_mov_b32_e32 v3, s70
	v_mov_b32_e32 v5, s71
	s_nop 1
	global_load_dword v2, v1, s[8:9] sc1
	global_load_dword v4, v3, s[8:9] sc1
	global_load_dword v6, v5, s[8:9] sc1
	v_readlane_b32 s5, v255, 2
	v_readlane_b32 s69, v255, 28
	s_waitcnt vmcnt(0)
	v_readfirstlane_b32 s1, v2
	v_readfirstlane_b32 s3, v4
	v_readfirstlane_b32 s4, v6
	s_and_b32 s5, s5, 7
	s_add_u32 s70, s5, 1
	s_sub_u32 s71, 8, s5
	s_cmp_lg_u32 s1, s70
	s_cbranch_scc1 .Lxb_bad0
	s_cmp_lg_u32 s3, s71
	s_cbranch_scc1 .Lxb_bad0
	s_cmp_lg_u32 s4, 32
	s_cbranch_scc1 .Lxb_bad0
	s_cmp_lg_u32 s69, 0x100
	s_cbranch_scc0 .Lxb_chkok0
.Lxb_bad0:
	v_mov_b32_e32 v1, 0x6000
	v_mov_b32_e32 v0, 1
	global_atomic_add v1, v0, s[8:9]
.Lxb_chkok0:
	s_mov_b64 exec, s[100:101]
	s_branch .Lxb_orig0
.Lxb_nochk0:
	s_cmp_lg_u32 s100, 1
	s_cbranch_scc1 .Lxb_orig0
	s_mov_b64 s[100:101], exec
	s_mov_b64 exec, 1
	s_waitcnt vmcnt(0) lgkmcnt(0)
	s_lshl_b32 s68, s0, 8
	v_readlane_b32 s8, v255, 19
	v_readlane_b32 s9, v255, 20
	s_add_u32 s69, s68, 0x1400
	s_add_u32 s70, s68, 0x2400
	v_mov_b32_e32 v0, 1
	v_mov_b32_e32 v1, s69
	s_nop 3
	global_atomic_add v2, v1, v0, s[8:9] sc0
	s_waitcnt vmcnt(0)
	v_readfirstlane_b32 s1, v2
	v_mov_b32_e32 v1, s70
	s_add_u32 s3, s1, 1
	s_and_b32 s3, s3, 31
	s_lshr_b32 s4, s1, 5
	s_cmp_eq_u32 s3, 0
	s_cbranch_scc1 .Lxb_rel0
	s_mov_b32 s5, 0
.Lxb_spin0:
	s_sleep 1
	global_load_dword v2, v1, s[8:9] sc1
	s_waitcnt vmcnt(0)
	v_readfirstlane_b32 s1, v2
	s_cmp_lg_u32 s1, s4
	s_cbranch_scc1 .Lxb_acq0
	s_add_u32 s5, s5, 1
	s_cmp_lt_u32 s5, 0x4000
	s_cbranch_scc1 .Lxb_spin0
	s_branch .Lxb_acq0
.Lxb_rel0:
	global_atomic_add v1, v0, s[8:9]
.Lxb_acq0:
	s_waitcnt vmcnt(0)
	buffer_inv sc1
	s_waitcnt vmcnt(0)
	s_mov_b64 exec, s[100:101]
	s_branch .LBB0_221
.Lxb_orig0:
	v_mbcnt_lo_u32_b32 v0, -1, 0
	v_mbcnt_hi_u32_b32 v0, -1, v0
	s_nop 0
	v_cmp_eq_u32_e32 vcc, 0, v0
	s_and_saveexec_b64 s[4:5], vcc
	s_cbranch_execz .LBB0_220
	v_readlane_b32 s1, v255, 38
	s_waitcnt vmcnt(0) expcnt(0) lgkmcnt(0)
	s_and_b32 s0, s0, 15
	v_mov_b32_e32 v0, s1
	ds_read_b32 v2, v0
	v_readlane_b32 s1, v255, 39
	s_lshl_b64 s[2:3], s[10:11], 2
	v_readlane_b32 s8, v255, 19
	v_mov_b32_e32 v0, s1
	ds_read_b32 v0, v0
	v_readlane_b32 s9, v255, 20
	s_add_u32 s64, s8, s2
	s_waitcnt lgkmcnt(1)
	v_cmp_ne_u32_e32 vcc, 0, v2
	s_addc_u32 s65, s9, s3
	s_cbranch_vccnz .LBB0_184
	v_readlane_b32 s8, v255, 0
	v_readlane_b32 s9, v255, 1
	s_add_u32 s66, s64, 0x1000
	s_load_dwordx2 s[2:3], s[8:9], 0x4
	s_addc_u32 s67, s65, 0
	s_add_u32 s68, s64, 0x1100
	s_addc_u32 s69, s65, 0
	s_add_u32 s70, s64, 0x1200
	v_readlane_b32 s1, v255, 28
	s_addc_u32 s71, s65, 0
	s_waitcnt lgkmcnt(0)
	s_mul_i32 s1, s2, s1
	s_add_u32 s72, s64, 0x1300
	s_mul_i32 s1, s1, s3
	s_addc_u32 s73, s65, 0
	s_mov_b32 s2, 1
	s_branch .LBB0_172

;     int tid_; asm volatile("v_mbcnt_lo_u32_b32 %0, -1, 0\n\tv_mbcnt_hi_u32_b32 %0, -1, %0" : "=v"(tid_)); tid_ += 64 * wave_id;
;     const int tid = tid_, wid = __builtin_amdgcn_readfirstlane(tid >> 6), lane = tid & 63, wr = wid >> 2, wc = wid & 3, fr = lane & 15, fq = lane >> 4;
;     const int K = KC ? KC : g.K, nt = K / BK;
;     unsigned voffA[2], voffB[2];
; #pragma unroll
;     for (int i = 0; i < 2; ++i) { int R, C; stage_rc(tid * 16 + i * 8192, R, C); const int Rb = Epi::PERM ? ((R & ~31) + perm32(R & 31)) : R;
;         voffA[i] = (unsigned)(R * K + C) * 2u; voffB[i] = (unsigned)(Rb * K + C) * 2u; }
;     const size_t kstep = (size_t)(BK * 2);
;     ...
;     const size_t hstep = (size_t)HALF * K * 2;
;     const size_t tstep = 2 * hstep;
;     const unsigned ldsw = (unsigned)wid * 1024u;
;     const int aoff = lds_byte(wr * 64 + fr, fq * 8), boff = lds_byte(wc * 32 + fr, fq * 8);
;     ...
;     Unit cur, nxt; int ui = 0;
;     if (!S.next(0, cur)) return;
;     f32x4 acc[2][2][4][2];
; #pragma unroll
;     for (int a = 0; a < 2; ++a)
; #pragma unroll
;         for (int b = 0; b < 2; ++b)
; #pragma unroll
;             for (int m = 0; m < 4; ++m)
; #pragma unroll
;                 for (int n = 0; n < 2; ++n) acc[a][b][m][n] = (f32x4){0.f, 0.f, 0.f, 0.f};
;     bf16x8 At[4][2], B0[2][2], B1[2][2];
;     const char* cA = (const char*)g.A + (size_t)cur.pm * tstep; const char* cB = (const char*)g.Bt + (size_t)cur.pn * tstep;
;     S.a_ready(cur);
;     if constexpr (SP2) {
;         PG8_STAGE(PG8_SB(0, 0), cB, voffB); PG8_STAGE(PG8_SB(0, 1), cB + hstep, voffB); PG8_STAGE(PG8_SA(0, 0), cA, voffA); PG8_STAGE(PG8_SA(0, 1), cA + hstep, voffA);
;         if (wr == 1) PG8_BAR;
;         PG8_WAIT_V(2); PG8_BAR;
;         PG8_STAGE(PG8_SB(1, 0), PG8_KADV(cB, kstep), voffB); PG8_STAGE(PG8_SA(1, 0), PG8_KADV(cA, kstep), voffA); PG8_STAGE(PG8_SB(1, 1), PG8_KADV(cB + hstep, kstep), voffB);
;         PG8_WAIT_V(6); PG8_BAR;
;     } else {
;         PG8_STAGE(PG8_SB(0, 0), cB, voffB); PG8_STAGE(PG8_SA(0, 0), cA, voffA); PG8_STAGE(PG8_SB(0, 1), cB + hstep, voffB); PG8_STAGE(PG8_SA(0, 1), cA + hstep, voffA);
;         if (wr == 1) PG8_BAR;
;         PG8_WAIT_V(4); PG8_BAR;
;         PG8_STAGE(PG8_SB(1, 0), PG8_KADV(cB, kstep), voffB); PG8_STAGE(PG8_SA(1, 0), PG8_KADV(cA, kstep), voffA); PG8_STAGE(PG8_SB(1, 1), PG8_KADV(cB + hstep, kstep), voffB);
.LBB0_221:
	s_add_u32 s64, s62, 0x24800000
	s_addc_u32 s65, s63, 0
	s_mul_i32 s92, s6, 0xa000000
	s_add_u32 s0, s62, s92
	s_addc_u32 s1, s63, 0
	s_add_u32 s31, s0, 0x4800000
	s_addc_u32 s0, s1, 0
	s_ashr_i32 s27, s50, 31
	s_cmpk_lt_i32 s50, 0xb00
	v_writelane_b32 v255, s0, 48
	s_cselect_b64 s[0:1], -1, 0
	s_waitcnt lgkmcnt(0)
	s_barrier
	s_cselect_b32 s100, 1, 0
	v_writelane_b32 v255, s100, 61
	v_readlane_b32 s100, v255, 60
	s_nop 1
	s_cmp_lg_u32 s100, 0
	s_cbranch_scc1 .Lxb_decided
	v_readlane_b32 s100, v255, 19
	v_readlane_b32 s101, v255, 20
	v_mov_b32_e32 v9, 0x6000
	s_nop 3
	global_load_dword v9, v9, s[100:101] sc1
	s_waitcnt vmcnt(0)
	v_readfirstlane_b32 s100, v9
	s_nop 1
	s_cmp_eq_u32 s100, 0
	s_cselect_b32 s100, 1, 2
	v_writelane_b32 v255, s100, 60
.Lxb_decided:
	v_readlane_b32 s100, v255, 61
	s_nop 1
	s_cmp_lg_u32 s100, 0
	v_mbcnt_lo_u32_b32 v9, -1, 0
	v_mbcnt_hi_u32_b32 v9, -1, v9
	v_writelane_b32 v255, s0, 49
	v_add_u32_e32 v0, s29, v9
	s_cmpk_gt_i32 s50, 0xaff
	v_writelane_b32 v255, s1, 50
	v_readfirstlane_b32 s5, v0
	s_cbranch_scc1 .LBB0_237
	v_lshlrev_b32_e32 v1, 4, v0
	v_add_u32_e32 v2, 0x2000, v1
	v_ashrrev_i32_e32 v3, 31, v2
	v_lshrrev_b32_e32 v3, 22, v3
	v_add_u32_e32 v3, v2, v3
	v_ashrrev_i32_e32 v8, 10, v3
	v_mul_i32_i24_e32 v3, 0x400, v8
	v_sub_u32_e32 v2, v2, v3
	v_lshrrev_b32_e32 v3, 4, v2
	v_bitop3_b32 v2, v3, v2, 32 bitop3:0x6c
	v_ashrrev_i32_e32 v3, 31, v2
	v_lshrrev_b32_e32 v3, 26, v3
	v_add_u32_e32 v3, v2, v3
	v_lshlrev_b32_e32 v4, 3, v8
	v_ashrrev_i32_e32 v10, 6, v3
	v_and_b32_e32 v4, -16, v4
	v_add_u32_e32 v4, v10, v4
	v_and_b32_e32 v5, 3, v10
	s_mov_b32 s1, 0xfffe0
	v_lshrrev_b32_e32 v6, 2, v4
	v_lshlrev_b32_e32 v7, 1, v4
	v_and_b32_e32 v3, 0xc0, v3
	v_and_or_b32 v5, v4, s1, v5
	v_and_b32_e32 v6, 4, v6
	v_and_b32_e32 v7, 24, v7
	v_sub_u32_e32 v2, v2, v3
	v_or3_b32 v5, v5, v6, v7
	v_lshlrev_b32_e32 v6, 5, v8
	v_ashrrev_i16_sdwa v2, v230, sext(v2) dst_sel:DWORD dst_unused:UNUSED_PAD src0_sel:DWORD src1_sel:BYTE_0
	v_and_b32_e32 v6, 32, v6
	v_bfe_i32 v11, v2, 0, 16
	v_add_lshl_u32 v2, v6, v11, 1
	v_lshl_add_u32 v128, v5, 12, v2
	v_lshl_add_u32 v130, v4, 12, v2
	v_bfe_i32 v2, v0, 27, 1
	v_lshrrev_b32_e32 v2, 22, v2
	v_add_u32_e32 v2, v1, v2
	v_and_b32_e32 v2, 0xfffffc00, v2
	v_sub_u32_e32 v1, v1, v2
	v_lshrrev_b32_e32 v2, 4, v1
	v_ashrrev_i32_e32 v3, 31, v0
	v_bitop3_b32 v1, v2, v1, 32 bitop3:0x6c
	v_lshrrev_b32_e32 v3, 26, v3
	v_ashrrev_i32_e32 v2, 31, v1
	v_add_u32_e32 v0, v0, v3
	v_lshrrev_b32_e32 v2, 26, v2
	v_ashrrev_i32_e32 v13, 6, v0
	v_add_u32_e32 v2, v1, v2
	v_lshlrev_b32_e32 v0, 3, v13
	v_ashrrev_i32_e32 v12, 6, v2
	v_and_b32_e32 v0, -16, v0
	v_add_u32_e32 v0, v12, v0
	v_and_b32_e32 v3, 3, v12
	v_and_or_b32 v3, v0, s1, v3
	s_lshr_b32 s1, s27, 29
	s_add_i32 s1, s50, s1
	s_ashr_i32 s9, s5, 6
	s_ashr_i32 s2, s1, 3
	s_and_b32 s1, s1, -8
	s_ashr_i32 s15, s5, 8
	s_lshl_b32 s0, s9, 10
	s_sub_i32 s1, s50, s1
	s_cmp_lt_i32 s1, 0
	s_movk_i32 s3, 0x161
	s_cselect_b32 s3, s3, 0x160
	s_mul_i32 s1, s3, s1
	s_add_i32 s1, s1, s2
	s_mul_hi_i32 s2, s1, 0x2e8ba2e9
	v_lshrrev_b32_e32 v4, 2, v0
	v_lshlrev_b32_e32 v5, 1, v0
	v_and_b32_e32 v2, 0xc0, v2
	s_lshr_b32 s3, s2, 31
	s_ashr_i32 s2, s2, 6
	v_and_b32_e32 v4, 4, v4
	v_and_b32_e32 v5, 24, v5
	v_sub_u32_e32 v1, v1, v2
	s_add_i32 s2, s2, s3
	v_or3_b32 v3, v3, v4, v5
	v_lshlrev_b32_e32 v4, 5, v13
	v_ashrrev_i16_sdwa v1, v230, sext(v1) dst_sel:DWORD dst_unused:UNUSED_PAD src0_sel:DWORD src1_sel:BYTE_0
	s_lshl_b32 s6, s2, 3
	v_and_b32_e32 v4, 32, v4
	v_bfe_i32 v14, v1, 0, 16
	s_sub_i32 s3, 64, s6
	v_add_lshl_u32 v1, v4, v14, 1
	s_min_u32 s7, s3, 8
	s_mulk_i32 s2, 0x160
	v_lshl_add_u32 v132, v3, 12, v1
	s_sub_i32 s1, s1, s2
	v_cvt_f32_ubyte0_e32 v3, s7
	v_cvt_f32_i32_e32 v2, s1
	v_rcp_iflag_f32_e32 v4, v3
	v_lshl_add_u32 v134, v0, 12, v1
	s_ashr_i32 s2, s1, 30
	s_or_b32 s4, s2, 1
	v_mul_f32_e32 v0, v2, v4
	v_trunc_f32_e32 v0, v0
	v_fma_f32 v1, -v0, v3, v2
	v_cvt_i32_f32_e32 v0, v0
	v_cmp_ge_f32_e64 s[2:3], |v1|, v3
	s_and_b64 s[2:3], s[2:3], exec
	s_cselect_b32 s2, s4, 0
	v_readfirstlane_b32 s3, v0
	s_add_i32 s4, s3, s2
	s_mul_i32 s2, s4, s7
	s_sub_i32 s1, s1, s2
	s_sext_i32_i16 s1, s1
	s_add_i32 s78, s6, s1
	s_ashr_i32 s79, s78, 31
	s_bfe_i64 s[6:7], s[4:5], 0x100000
	s_lshl_b64 s[2:3], s[78:79], 20
	s_lshl_b64 s[6:7], s[6:7], 20
	s_add_u32 s82, s31, s6
	v_readlane_b32 s1, v255, 48
	s_addc_u32 s83, s1, s7
	s_add_i32 s1, s0, 0
	s_add_i32 m0, s1, 0x10000
	v_mov_b32_e32 v133, v169
	global_load_lds_dwordx4 v132, s[82:83]
	s_add_i32 m0, s1, 0x12000
	s_add_u32 s6, s82, 0x80000
	global_load_lds_dwordx4 v128, s[82:83]
	s_addc_u32 s7, s83, 0
	s_add_i32 m0, s1, 0x14000
	v_mov_b32_e32 v129, v169
	global_load_lds_dwordx4 v132, s[6:7]
	s_add_i32 m0, s1, 0x16000
	s_add_u32 s80, s54, s2
	s_addc_u32 s81, s55, s3
	s_add_i32 s2, s1, 0x2000
	global_load_lds_dwordx4 v128, s[6:7]
	s_mov_b32 m0, s1
	s_add_u32 s6, s80, 0x80000
	global_load_lds_dwordx4 v134, s[80:81]
	s_mov_b32 m0, s2
	s_addc_u32 s7, s81, 0
	s_add_i32 s3, s1, 0x4000
	global_load_lds_dwordx4 v130, s[80:81]
	s_mov_b32 m0, s3
	s_add_i32 s8, s1, 0x6000
	global_load_lds_dwordx4 v134, s[6:7]
	s_mov_b32 m0, s8
	v_mov_b32_e32 v135, v169
	global_load_lds_dwordx4 v130, s[6:7]
	v_mov_b32_e32 v131, v169
	s_cmp_eq_u32 s15, 1
	v_lshl_add_u64 v[6:7], s[82:83], 0, v[132:133]
	v_lshl_add_u64 v[4:5], s[82:83], 0, v[128:129]
	v_lshl_add_u64 v[0:1], s[80:81], 0, v[134:135]
	s_cselect_b64 s[6:7], -1, 0
	s_cmp_lg_u32 s15, 1
	v_lshl_add_u64 v[2:3], s[80:81], 0, v[130:131]
	s_cbranch_scc1 .LBB0_224
	s_barrier

; __device__ __forceinline__ unsigned xb_ld(unsigned* p)              { return __hip_atomic_load(p, __ATOMIC_RELAXED, __HIP_MEMORY_SCOPE_AGENT); }
; __device__ __forceinline__ unsigned xb_add(unsigned* p, unsigned v) { return __hip_atomic_fetch_add(p, v, __ATOMIC_RELAXED, __HIP_MEMORY_SCOPE_AGENT); }
; #define XB_SPIN(cond, bar) do { unsigned _sp = 0; while (cond) { __builtin_amdgcn_s_sleep(1); \
;     if ((++_sp & 255u) == 0u) { if (xb_ld(&(bar)[XB_TMO])) break; if (_sp > XB_SPIN_CAP) { atomicAdd(&(bar)[XB_TMO], 1u); break; } } } } while (0)
; __device__ __forceinline__ int xb_lane() { int l; asm volatile("v_mbcnt_lo_u32_b32 %0, -1, 0\n\tv_mbcnt_hi_u32_b32 %0, -1, %0" : "=v"(l)); return l; }
; __device__ __forceinline__ void xcd_barrier(const XcdBarrier& b) {
;     asm volatile("s_waitcnt vmcnt(0)" ::: "memory");
;     __syncthreads();
;     if (b.wv == 0 && xb_lane() == 0) {
;         unsigned* bar = b.bar;
;         __builtin_amdgcn_s_waitcnt(0);
;         unsigned nloc = b.st[0], nx = b.st[1];
;         if (nloc == 0u) { xcd_barrier_complete(bar, b.x, nloc, nx); b.st[0] = nloc; b.st[1] = nx; }
;         const unsigned old = xb_add(&bar[XB_XSUB(b.x)], 1u);
;         const unsigned gen = old / nloc;
;         if (old + 1u == (gen + 1u) * nloc) {
;             __builtin_amdgcn_fence(__ATOMIC_RELEASE, "agent");
;             asm volatile("s_waitcnt vmcnt(0)" ::: "memory");
;             const unsigned og = xb_add(&bar[XB_TOP], 1u);
;             const unsigned tg = og / nx;
;             if (og + 1u == (tg + 1u) * nx) xb_add(&bar[XB_TOPGEN], 1u);
;             else XB_SPIN(xb_ld(&bar[XB_TOPGEN]) == tg, bar);
;             __builtin_amdgcn_fence(__ATOMIC_ACQUIRE, "agent");
;             xb_add(&bar[XB_XGEN(b.x)], 1u);
;             asm volatile("s_waitcnt vmcnt(0)" ::: "memory");
;         } else {
;             XB_SPIN(xb_ld(&bar[XB_XGEN(b.x)]) == gen, bar);
;             __builtin_amdgcn_fence(__ATOMIC_ACQUIRE, "agent");
;             asm volatile("s_waitcnt vmcnt(0)" ::: "memory");
;         }
;     }
;     __syncthreads();
; }
.LBB0_237:
	s_mov_b32 s10, s11
	s_getreg_b32 s0, hwreg(HW_REG_XCC_ID, 0, 4)
	s_waitcnt vmcnt(0)
	v_readlane_b32 s2, v255, 46
	v_readlane_b32 s3, v255, 47
	s_and_b64 vcc, exec, s[2:3]
	s_waitcnt vmcnt(0)
	s_barrier
	s_cbranch_vccnz .LBB0_291
	v_readlane_b32 s100, v255, 60
	s_nop 1
	s_cmp_lg_u32 s100, 1
	s_cbranch_scc1 .Lxb_orig1
	s_mov_b64 s[100:101], exec
	s_mov_b64 exec, 1
	s_waitcnt vmcnt(0) lgkmcnt(0)
	s_lshl_b32 s68, s0, 8
	v_readlane_b32 s8, v255, 19
	v_readlane_b32 s9, v255, 20
	s_add_u32 s69, s68, 0x1400
	s_add_u32 s70, s68, 0x2400
	v_mov_b32_e32 v0, 1
	v_mov_b32_e32 v1, s69
	s_nop 3
	global_atomic_add v2, v1, v0, s[8:9] sc0
	s_waitcnt vmcnt(0)
	v_readfirstlane_b32 s1, v2
	v_mov_b32_e32 v1, s70
	s_add_u32 s3, s1, 1
	s_and_b32 s3, s3, 31
	s_lshr_b32 s4, s1, 5
	s_cmp_eq_u32 s3, 0
	s_cbranch_scc1 .Lxb_rel1
	s_mov_b32 s5, 0

; __device__ __forceinline__ unsigned xb_ld(unsigned* p)              { return __hip_atomic_load(p, __ATOMIC_RELAXED, __HIP_MEMORY_SCOPE_AGENT); }
; __device__ __forceinline__ unsigned xb_add(unsigned* p, unsigned v) { return __hip_atomic_fetch_add(p, v, __ATOMIC_RELAXED, __HIP_MEMORY_SCOPE_AGENT); }
; __device__ __forceinline__ int xb_lane() { int l; asm volatile("v_mbcnt_lo_u32_b32 %0, -1, 0\n\tv_mbcnt_hi_u32_b32 %0, -1, %0" : "=v"(l)); return l; }
; __device__ __forceinline__ void xcd_barrier_complete(unsigned* bar, unsigned x, unsigned& nloc, unsigned& nx) {
;     const unsigned G = gridDim.x * gridDim.y * gridDim.z;
;     unsigned sum, cnt, mine, sp = 0u;
;     for (;;) {
;         sum = 0u; cnt = 0u; mine = 0u;
; #pragma unroll
;         for (unsigned j = 0; j < 16; ++j) { const unsigned c = xb_ld(&bar[XB_XCNT(j)]); sum += c; cnt += (c > 0u) ? 1u : 0u; mine = (j == x) ? c : mine; }
;         if (sum == G) break;
;         __builtin_amdgcn_s_sleep(1);
;         if ((++sp & 255u) == 0u) { if (xb_ld(&bar[XB_TMO])) break; if (sp > XB_SPIN_CAP) { atomicAdd(&bar[XB_TMO], 1u); break; } }
;     }
;     nloc = mine > 0u ? mine : 1u; nx = cnt > 0u ? cnt : 1u;
; }
; __device__ __forceinline__ void xcd_barrier(const XcdBarrier& b) {
;     asm volatile("s_waitcnt vmcnt(0)" ::: "memory");
;     __syncthreads();
;     if (b.wv == 0 && xb_lane() == 0) {
;         unsigned* bar = b.bar;
;         __builtin_amdgcn_s_waitcnt(0);
;         unsigned nloc = b.st[0], nx = b.st[1];
;         if (nloc == 0u) { xcd_barrier_complete(bar, b.x, nloc, nx); b.st[0] = nloc; b.st[1] = nx; }
;         const unsigned old = xb_add(&bar[XB_XSUB(b.x)], 1u);
.Lxb_orig1:
	v_mbcnt_lo_u32_b32 v0, -1, 0
	v_mbcnt_hi_u32_b32 v0, -1, v0
	s_nop 0
	v_cmp_eq_u32_e32 vcc, 0, v0
	s_and_saveexec_b64 s[4:5], vcc
	s_cbranch_execz .LBB0_290
	v_readlane_b32 s1, v255, 38
	s_waitcnt vmcnt(0) expcnt(0) lgkmcnt(0)
	s_and_b32 s0, s0, 15
	v_mov_b32_e32 v0, s1
	ds_read_b32 v2, v0
	v_readlane_b32 s1, v255, 39
	s_lshl_b64 s[2:3], s[10:11], 2
	v_readlane_b32 s6, v255, 19
	v_mov_b32_e32 v0, s1
	ds_read_b32 v0, v0
	v_readlane_b32 s7, v255, 20
	s_add_u32 s6, s6, s2
	s_waitcnt lgkmcnt(1)
	v_cmp_ne_u32_e32 vcc, 0, v2
	s_addc_u32 s7, s7, s3
	s_cbranch_vccnz .LBB0_254
	v_readlane_b32 s8, v255, 0
	v_readlane_b32 s9, v255, 1
	s_add_u32 s68, s6, 0x1000
	s_load_dwordx2 s[2:3], s[8:9], 0x4
	s_addc_u32 s69, s7, 0
	s_add_u32 s70, s6, 0x1100
	s_addc_u32 s71, s7, 0
	s_add_u32 s72, s6, 0x1200
	v_readlane_b32 s1, v255, 28
	s_addc_u32 s73, s7, 0
	s_waitcnt lgkmcnt(0)
	s_mul_i32 s1, s2, s1
	s_add_u32 s74, s6, 0x1300
	s_mul_i32 s1, s1, s3
	s_addc_u32 s75, s7, 0
	s_mov_b32 s2, 1
	s_branch .LBB0_242

; __device__ __forceinline__ unsigned xb_ld(unsigned* p)              { return __hip_atomic_load(p, __ATOMIC_RELAXED, __HIP_MEMORY_SCOPE_AGENT); }
; __device__ __forceinline__ unsigned xb_add(unsigned* p, unsigned v) { return __hip_atomic_fetch_add(p, v, __ATOMIC_RELAXED, __HIP_MEMORY_SCOPE_AGENT); }
; __device__ __forceinline__ int xb_lane() { int l; asm volatile("v_mbcnt_lo_u32_b32 %0, -1, 0\n\tv_mbcnt_hi_u32_b32 %0, -1, %0" : "=v"(l)); return l; }
; __device__ __forceinline__ void xcd_barrier_complete(unsigned* bar, unsigned x, unsigned& nloc, unsigned& nx) {
;     const unsigned G = gridDim.x * gridDim.y * gridDim.z;
;     unsigned sum, cnt, mine, sp = 0u;
;     for (;;) {
;         sum = 0u; cnt = 0u; mine = 0u;
; #pragma unroll
;         for (unsigned j = 0; j < 16; ++j) { const unsigned c = xb_ld(&bar[XB_XCNT(j)]); sum += c; cnt += (c > 0u) ? 1u : 0u; mine = (j == x) ? c : mine; }
;         if (sum == G) break;
;         __builtin_amdgcn_s_sleep(1);
;         if ((++sp & 255u) == 0u) { if (xb_ld(&bar[XB_TMO])) break; if (sp > XB_SPIN_CAP) { atomicAdd(&bar[XB_TMO], 1u); break; } }
;     }
;     nloc = mine > 0u ? mine : 1u; nx = cnt > 0u ? cnt : 1u;
; }
; __device__ __forceinline__ void xcd_barrier(const XcdBarrier& b) {
;     asm volatile("s_waitcnt vmcnt(0)" ::: "memory");
;     __syncthreads();
;     if (b.wv == 0 && xb_lane() == 0) {
;         unsigned* bar = b.bar;
;         __builtin_amdgcn_s_waitcnt(0);
;         unsigned nloc = b.st[0], nx = b.st[1];
;         if (nloc == 0u) { xcd_barrier_complete(bar, b.x, nloc, nx); b.st[0] = nloc; b.st[1] = nx; }
;         const unsigned old = xb_add(&bar[XB_XSUB(b.x)], 1u);
.Lxb_orig2:
	v_mbcnt_lo_u32_b32 v0, -1, 0
	v_mbcnt_hi_u32_b32 v0, -1, v0
	s_nop 0
	v_cmp_eq_u32_e32 vcc, 0, v0
	s_and_saveexec_b64 s[4:5], vcc
	s_cbranch_execz .LBB0_916
	v_readlane_b32 s1, v255, 38
	s_waitcnt vmcnt(0) expcnt(0) lgkmcnt(0)
	s_and_b32 s0, s0, 15
	v_mov_b32_e32 v0, s1
	ds_read_b32 v2, v0
	v_readlane_b32 s1, v255, 39
	s_lshl_b64 s[2:3], s[10:11], 2
	v_readlane_b32 s8, v255, 19
	v_mov_b32_e32 v0, s1
	ds_read_b32 v0, v0
	v_readlane_b32 s9, v255, 20
	s_add_u32 s60, s8, s2
	s_waitcnt lgkmcnt(1)
	v_cmp_ne_u32_e32 vcc, 0, v2
	s_addc_u32 s61, s9, s3
	s_cbranch_vccnz .LBB0_880
	v_readlane_b32 s8, v255, 0
	v_readlane_b32 s9, v255, 1
	s_add_u32 s62, s60, 0x1000
	s_load_dwordx2 s[2:3], s[8:9], 0x4
	s_addc_u32 s63, s61, 0
	s_add_u32 s68, s60, 0x1100
	s_addc_u32 s69, s61, 0
	s_add_u32 s70, s60, 0x1200
	v_readlane_b32 s1, v255, 28
	s_addc_u32 s71, s61, 0
	s_waitcnt lgkmcnt(0)
	s_mul_i32 s1, s2, s1
	s_add_u32 s72, s60, 0x1300
	s_mul_i32 s1, s1, s3
	s_addc_u32 s73, s61, 0
	s_mov_b32 s2, 1
	s_branch .LBB0_868

; __device__ __forceinline__ unsigned xb_ld(unsigned* p)              { return __hip_atomic_load(p, __ATOMIC_RELAXED, __HIP_MEMORY_SCOPE_AGENT); }
; __device__ __forceinline__ unsigned xb_add(unsigned* p, unsigned v) { return __hip_atomic_fetch_add(p, v, __ATOMIC_RELAXED, __HIP_MEMORY_SCOPE_AGENT); }
; #define XB_SPIN(cond, bar) do { unsigned _sp = 0; while (cond) { __builtin_amdgcn_s_sleep(1); \
;     if ((++_sp & 255u) == 0u) { if (xb_ld(&(bar)[XB_TMO])) break; if (_sp > XB_SPIN_CAP) { atomicAdd(&(bar)[XB_TMO], 1u); break; } } } } while (0)
; __device__ __forceinline__ int xb_lane() { int l; asm volatile("v_mbcnt_lo_u32_b32 %0, -1, 0\n\tv_mbcnt_hi_u32_b32 %0, -1, %0" : "=v"(l)); return l; }
; __device__ __forceinline__ void xcd_barrier(const XcdBarrier& b) {
;     asm volatile("s_waitcnt vmcnt(0)" ::: "memory");
;     __syncthreads();
;     if (b.wv == 0 && xb_lane() == 0) {
;         unsigned* bar = b.bar;
;         __builtin_amdgcn_s_waitcnt(0);
;         unsigned nloc = b.st[0], nx = b.st[1];
;         if (nloc == 0u) { xcd_barrier_complete(bar, b.x, nloc, nx); b.st[0] = nloc; b.st[1] = nx; }
;         const unsigned old = xb_add(&bar[XB_XSUB(b.x)], 1u);
;         const unsigned gen = old / nloc;
;         if (old + 1u == (gen + 1u) * nloc) {
;             __builtin_amdgcn_fence(__ATOMIC_RELEASE, "agent");
;             asm volatile("s_waitcnt vmcnt(0)" ::: "memory");
;             const unsigned og = xb_add(&bar[XB_TOP], 1u);
;             const unsigned tg = og / nx;
;             if (og + 1u == (tg + 1u) * nx) xb_add(&bar[XB_TOPGEN], 1u);
;             else XB_SPIN(xb_ld(&bar[XB_TOPGEN]) == tg, bar);
;             __builtin_amdgcn_fence(__ATOMIC_ACQUIRE, "agent");
;             xb_add(&bar[XB_XGEN(b.x)], 1u);
;             asm volatile("s_waitcnt vmcnt(0)" ::: "memory");
;         } else {
;             XB_SPIN(xb_ld(&bar[XB_XGEN(b.x)]) == gen, bar);
;             __builtin_amdgcn_fence(__ATOMIC_ACQUIRE, "agent");
;             asm volatile("s_waitcnt vmcnt(0)" ::: "memory");
;         }
;     }
;     __syncthreads();
; }
.LBB0_920:
	s_mov_b32 s10, s11
	s_getreg_b32 s2, hwreg(HW_REG_XCC_ID, 0, 4)
	s_waitcnt vmcnt(0)
	v_readlane_b32 s0, v255, 46
	v_readlane_b32 s1, v255, 47
	s_and_b64 vcc, exec, s[0:1]
	s_barrier
	s_cbranch_vccnz .LBB0_974
	v_readlane_b32 s100, v255, 60
	s_nop 1
	s_cmp_lg_u32 s100, 1
	s_cbranch_scc1 .Lxb_orig3
	s_mov_b64 s[100:101], exec
	s_mov_b64 exec, 1
	s_waitcnt vmcnt(0) lgkmcnt(0)
	s_lshl_b32 s68, s2, 8
	v_readlane_b32 s8, v255, 19
	v_readlane_b32 s9, v255, 20
	s_add_u32 s69, s68, 0x1400
	s_add_u32 s70, s68, 0x2400
	v_mov_b32_e32 v0, 1
	v_mov_b32_e32 v1, s69
	s_nop 3
	global_atomic_add v2, v1, v0, s[8:9] sc0
	s_waitcnt vmcnt(0)
	v_readfirstlane_b32 s1, v2
	v_mov_b32_e32 v1, s70
	s_add_u32 s3, s1, 1
	s_and_b32 s3, s3, 31
	s_lshr_b32 s4, s1, 5
	s_cmp_eq_u32 s3, 0
	s_cbranch_scc1 .Lxb_rel3
	s_mov_b32 s5, 0

; __device__ __forceinline__ unsigned xb_ld(unsigned* p)              { return __hip_atomic_load(p, __ATOMIC_RELAXED, __HIP_MEMORY_SCOPE_AGENT); }
; __device__ __forceinline__ unsigned xb_add(unsigned* p, unsigned v) { return __hip_atomic_fetch_add(p, v, __ATOMIC_RELAXED, __HIP_MEMORY_SCOPE_AGENT); }
; __device__ __forceinline__ int xb_lane() { int l; asm volatile("v_mbcnt_lo_u32_b32 %0, -1, 0\n\tv_mbcnt_hi_u32_b32 %0, -1, %0" : "=v"(l)); return l; }
; __device__ __forceinline__ void xcd_barrier_complete(unsigned* bar, unsigned x, unsigned& nloc, unsigned& nx) {
;     const unsigned G = gridDim.x * gridDim.y * gridDim.z;
;     unsigned sum, cnt, mine, sp = 0u;
;     for (;;) {
;         sum = 0u; cnt = 0u; mine = 0u;
; #pragma unroll
;         for (unsigned j = 0; j < 16; ++j) { const unsigned c = xb_ld(&bar[XB_XCNT(j)]); sum += c; cnt += (c > 0u) ? 1u : 0u; mine = (j == x) ? c : mine; }
;         if (sum == G) break;
;         __builtin_amdgcn_s_sleep(1);
;         if ((++sp & 255u) == 0u) { if (xb_ld(&bar[XB_TMO])) break; if (sp > XB_SPIN_CAP) { atomicAdd(&bar[XB_TMO], 1u); break; } }
;     }
;     nloc = mine > 0u ? mine : 1u; nx = cnt > 0u ? cnt : 1u;
; }
; __device__ __forceinline__ void xcd_barrier(const XcdBarrier& b) {
;     asm volatile("s_waitcnt vmcnt(0)" ::: "memory");
;     __syncthreads();
;     if (b.wv == 0 && xb_lane() == 0) {
;         unsigned* bar = b.bar;
;         __builtin_amdgcn_s_waitcnt(0);
;         unsigned nloc = b.st[0], nx = b.st[1];
;         if (nloc == 0u) { xcd_barrier_complete(bar, b.x, nloc, nx); b.st[0] = nloc; b.st[1] = nx; }
;         const unsigned old = xb_add(&bar[XB_XSUB(b.x)], 1u);
.Lxb_orig3:
	v_mbcnt_lo_u32_b32 v0, -1, 0
	v_mbcnt_hi_u32_b32 v0, -1, v0
	s_nop 0
	v_cmp_eq_u32_e32 vcc, 0, v0
	s_and_saveexec_b64 s[0:1], vcc
	s_cbranch_execz .LBB0_973
	v_readlane_b32 s3, v255, 38
	s_waitcnt vmcnt(0) expcnt(0) lgkmcnt(0)
	s_and_b32 s2, s2, 15
	v_mov_b32_e32 v0, s3
	ds_read_b32 v2, v0
	v_readlane_b32 s3, v255, 39
	s_lshl_b64 s[4:5], s[10:11], 2
	v_readlane_b32 s8, v255, 19
	v_mov_b32_e32 v0, s3
	ds_read_b32 v0, v0
	v_readlane_b32 s9, v255, 20
	s_add_u32 s4, s8, s4
	s_waitcnt lgkmcnt(1)
	v_cmp_ne_u32_e32 vcc, 0, v2
	s_addc_u32 s5, s9, s5
	s_cbranch_vccnz .LBB0_937
	v_readlane_b32 s12, v255, 0
	v_readlane_b32 s13, v255, 1
	s_add_u32 s56, s4, 0x1000
	s_load_dwordx2 s[8:9], s[12:13], 0x4
	s_addc_u32 s57, s5, 0
	s_add_u32 s58, s4, 0x1100
	s_addc_u32 s59, s5, 0
	s_add_u32 s60, s4, 0x1200
	v_readlane_b32 s3, v255, 28
	s_addc_u32 s61, s5, 0
	s_waitcnt lgkmcnt(0)
	s_mul_i32 s3, s8, s3
	s_add_u32 s62, s4, 0x1300
	s_mul_i32 s3, s3, s9
	s_addc_u32 s63, s5, 0
	s_mov_b32 s8, 1
	s_branch .LBB0_925

; __device__ __forceinline__ unsigned xb_ld(unsigned* p)              { return __hip_atomic_load(p, __ATOMIC_RELAXED, __HIP_MEMORY_SCOPE_AGENT); }
; __device__ __forceinline__ unsigned xb_add(unsigned* p, unsigned v) { return __hip_atomic_fetch_add(p, v, __ATOMIC_RELAXED, __HIP_MEMORY_SCOPE_AGENT); }
; #define XB_SPIN(cond, bar) do { unsigned _sp = 0; while (cond) { __builtin_amdgcn_s_sleep(1); \
;     if ((++_sp & 255u) == 0u) { if (xb_ld(&(bar)[XB_TMO])) break; if (_sp > XB_SPIN_CAP) { atomicAdd(&(bar)[XB_TMO], 1u); break; } } } } while (0)
; __device__ __forceinline__ int xb_lane() { int l; asm volatile("v_mbcnt_lo_u32_b32 %0, -1, 0\n\tv_mbcnt_hi_u32_b32 %0, -1, %0" : "=v"(l)); return l; }
; __device__ __forceinline__ void xcd_barrier(const XcdBarrier& b) {
;     asm volatile("s_waitcnt vmcnt(0)" ::: "memory");
;     __syncthreads();
;     if (b.wv == 0 && xb_lane() == 0) {
;         unsigned* bar = b.bar;
;         __builtin_amdgcn_s_waitcnt(0);
;         unsigned nloc = b.st[0], nx = b.st[1];
;         if (nloc == 0u) { xcd_barrier_complete(bar, b.x, nloc, nx); b.st[0] = nloc; b.st[1] = nx; }
;         const unsigned old = xb_add(&bar[XB_XSUB(b.x)], 1u);
;         const unsigned gen = old / nloc;
;         if (old + 1u == (gen + 1u) * nloc) {
;             __builtin_amdgcn_fence(__ATOMIC_RELEASE, "agent");
;             asm volatile("s_waitcnt vmcnt(0)" ::: "memory");
;             const unsigned og = xb_add(&bar[XB_TOP], 1u);
;             const unsigned tg = og / nx;
;             if (og + 1u == (tg + 1u) * nx) xb_add(&bar[XB_TOPGEN], 1u);
;             else XB_SPIN(xb_ld(&bar[XB_TOPGEN]) == tg, bar);
;             __builtin_amdgcn_fence(__ATOMIC_ACQUIRE, "agent");
;             xb_add(&bar[XB_XGEN(b.x)], 1u);
;             asm volatile("s_waitcnt vmcnt(0)" ::: "memory");
;         } else {
;             XB_SPIN(xb_ld(&bar[XB_XGEN(b.x)]) == gen, bar);
;             __builtin_amdgcn_fence(__ATOMIC_ACQUIRE, "agent");
;             asm volatile("s_waitcnt vmcnt(0)" ::: "memory");
;         }
;     }
;     __syncthreads();
; }
.LBB0_990:
	s_mov_b32 s10, s11
	s_getreg_b32 s2, hwreg(HW_REG_XCC_ID, 0, 4)
	s_waitcnt vmcnt(0)
	v_readlane_b32 s0, v255, 46
	v_readlane_b32 s1, v255, 47
	s_and_b64 vcc, exec, s[0:1]
	s_waitcnt vmcnt(0)
	s_barrier
	s_cbranch_vccnz .LBB0_1045
	v_readlane_b32 s100, v255, 60
	s_nop 1
	s_cmp_lg_u32 s100, 1
	s_cbranch_scc1 .Lxb_orig4
	s_mov_b64 s[100:101], exec
	s_mov_b64 exec, 1
	s_waitcnt vmcnt(0) lgkmcnt(0)
	s_lshl_b32 s68, s2, 8
	v_readlane_b32 s8, v255, 19
	v_readlane_b32 s9, v255, 20
	s_add_u32 s69, s68, 0x1400
	s_add_u32 s70, s68, 0x2400
	v_mov_b32_e32 v0, 1
	v_mov_b32_e32 v1, s69
	s_nop 3
	global_atomic_add v2, v1, v0, s[8:9] sc0
	s_waitcnt vmcnt(0)
	v_readfirstlane_b32 s1, v2
	v_mov_b32_e32 v1, s70
	s_add_u32 s3, s1, 1
	s_and_b32 s3, s3, 31
	s_lshr_b32 s4, s1, 5
	s_cmp_eq_u32 s3, 0
	s_cbranch_scc1 .Lxb_rel4
	s_mov_b32 s5, 0

; __device__ __forceinline__ unsigned xb_ld(unsigned* p)              { return __hip_atomic_load(p, __ATOMIC_RELAXED, __HIP_MEMORY_SCOPE_AGENT); }
; __device__ __forceinline__ unsigned xb_add(unsigned* p, unsigned v) { return __hip_atomic_fetch_add(p, v, __ATOMIC_RELAXED, __HIP_MEMORY_SCOPE_AGENT); }
; __device__ __forceinline__ int xb_lane() { int l; asm volatile("v_mbcnt_lo_u32_b32 %0, -1, 0\n\tv_mbcnt_hi_u32_b32 %0, -1, %0" : "=v"(l)); return l; }
; __device__ __forceinline__ void xcd_barrier_complete(unsigned* bar, unsigned x, unsigned& nloc, unsigned& nx) {
;     const unsigned G = gridDim.x * gridDim.y * gridDim.z;
;     unsigned sum, cnt, mine, sp = 0u;
;     for (;;) {
;         sum = 0u; cnt = 0u; mine = 0u;
; #pragma unroll
;         for (unsigned j = 0; j < 16; ++j) { const unsigned c = xb_ld(&bar[XB_XCNT(j)]); sum += c; cnt += (c > 0u) ? 1u : 0u; mine = (j == x) ? c : mine; }
;         if (sum == G) break;
;         __builtin_amdgcn_s_sleep(1);
;         if ((++sp & 255u) == 0u) { if (xb_ld(&bar[XB_TMO])) break; if (sp > XB_SPIN_CAP) { atomicAdd(&bar[XB_TMO], 1u); break; } }
;     }
;     nloc = mine > 0u ? mine : 1u; nx = cnt > 0u ? cnt : 1u;
; }
; __device__ __forceinline__ void xcd_barrier(const XcdBarrier& b) {
;     asm volatile("s_waitcnt vmcnt(0)" ::: "memory");
;     __syncthreads();
;     if (b.wv == 0 && xb_lane() == 0) {
;         unsigned* bar = b.bar;
;         __builtin_amdgcn_s_waitcnt(0);
;         unsigned nloc = b.st[0], nx = b.st[1];
;         if (nloc == 0u) { xcd_barrier_complete(bar, b.x, nloc, nx); b.st[0] = nloc; b.st[1] = nx; }
;         const unsigned old = xb_add(&bar[XB_XSUB(b.x)], 1u);
.Lxb_orig4:
	v_mbcnt_lo_u32_b32 v0, -1, 0
	v_mbcnt_hi_u32_b32 v0, -1, v0
	s_nop 0
	v_cmp_eq_u32_e32 vcc, 0, v0
	s_and_saveexec_b64 s[0:1], vcc
	s_cbranch_execz .LBB0_1044
	v_readlane_b32 s3, v255, 38
	s_waitcnt vmcnt(0) expcnt(0) lgkmcnt(0)
	s_and_b32 s2, s2, 15
	v_mov_b32_e32 v0, s3
	ds_read_b32 v2, v0
	v_readlane_b32 s3, v255, 39
	s_lshl_b64 s[4:5], s[10:11], 2
	v_readlane_b32 s8, v255, 19
	v_mov_b32_e32 v0, s3
	ds_read_b32 v0, v0
	v_readlane_b32 s9, v255, 20
	s_add_u32 s4, s8, s4
	s_waitcnt lgkmcnt(1)
	v_cmp_ne_u32_e32 vcc, 0, v2
	s_addc_u32 s5, s9, s5
	s_cbranch_vccnz .LBB0_1008
	v_readlane_b32 s12, v255, 0
	v_readlane_b32 s13, v255, 1
	s_add_u32 s54, s4, 0x1000
	s_load_dwordx2 s[8:9], s[12:13], 0x4
	s_addc_u32 s55, s5, 0
	s_add_u32 s56, s4, 0x1100
	s_addc_u32 s57, s5, 0
	s_add_u32 s58, s4, 0x1200
	v_readlane_b32 s3, v255, 28
	s_addc_u32 s59, s5, 0
	s_waitcnt lgkmcnt(0)
	s_mul_i32 s3, s8, s3
	s_add_u32 s60, s4, 0x1300
	s_mul_i32 s3, s3, s9
	s_addc_u32 s61, s5, 0
	s_mov_b32 s8, 1
	s_branch .LBB0_996
